# DeepNorm-residual GEMM epilogues (phases 6,13): residual-row loads hoisted (14 in flight) instead of 8 serialized load-wait-store rounds
# speedup vs baseline: 1.1073x; 1.0122x over previous
.LBB0_631:
	s_setprio 1
	ds_read_b128 v[146:149], v128
	ds_read_b128 v[154:157], v143 offset:23040
	ds_read_b128 v[150:153], v128 offset:4608
	ds_read_b128 v[158:161], v128 offset:32
	s_add_i32 s14, s40, 0xc0
	s_cmpk_lt_u32 s40, 0x340
	s_cselect_b32 s14, s14, 0x3c0
	s_lshl_b64 s[42:43], s[14:15], 1
	s_waitcnt lgkmcnt(2)
	v_mfma_f32_32x32x16_bf16 v[32:47], v[146:149], v[154:157], v[32:47]
	ds_read_b128 v[162:165], v143 offset:18432
	v_lshl_add_u64 v[166:167], v[130:131], 0, s[42:43]
	v_lshl_add_u64 v[168:169], v[132:133], 0, s[42:43]
	v_lshl_add_u64 v[174:175], v[166:167], 0, v[134:135]
	v_lshl_add_u64 v[182:183], v[168:169], 0, v[134:135]
	v_lshl_add_u64 v[184:185], v[166:167], 0, v[136:137]
	v_lshl_add_u64 v[186:187], v[168:169], 0, v[136:137]
	v_lshl_add_u64 v[188:189], v[166:167], 0, v[138:139]
	v_lshl_add_u64 v[190:191], v[168:169], 0, v[138:139]
	v_lshl_add_u64 v[192:193], v[166:167], 0, v[140:141]
	s_waitcnt lgkmcnt(0)
	v_mfma_f32_32x32x16_bf16 v[48:63], v[146:149], v[162:165], v[48:63]
	ds_read_b128 v[146:149], v143 offset:18464
	v_lshl_add_u64 v[194:195], v[168:169], 0, v[140:141]
	v_mfma_f32_32x32x16_bf16 v[16:31], v[150:153], v[162:165], v[16:31]
	ds_read_b128 v[162:165], v128 offset:4640
	v_mfma_f32_32x32x16_bf16 v[0:15], v[150:153], v[154:157], v[0:15]
	ds_read_b128 v[150:153], v143 offset:23072
	s_waitcnt lgkmcnt(2)
	v_mfma_f32_32x32x16_bf16 v[48:63], v[158:161], v[146:149], v[48:63]
	ds_read_b128 v[154:157], v128 offset:64
	s_waitcnt lgkmcnt(1)
	v_mfma_f32_32x32x16_bf16 v[32:47], v[158:161], v[150:153], v[32:47]
	ds_read_b128 v[158:161], v143 offset:18496
	v_mfma_f32_32x32x16_bf16 v[16:31], v[162:165], v[146:149], v[16:31]
	ds_read_b128 v[146:149], v128 offset:4672
	v_mfma_f32_32x32x16_bf16 v[0:15], v[162:165], v[150:153], v[0:15]
	ds_read_b128 v[150:153], v143 offset:23104
	s_waitcnt lgkmcnt(2)
	v_mfma_f32_32x32x16_bf16 v[48:63], v[154:157], v[158:161], v[48:63]
	ds_read_b128 v[162:165], v128 offset:96
	ds_read_b128 v[166:169], v143 offset:18528
	ds_read_b128 v[170:173], v128 offset:4704
	ds_read_b128 v[178:181], v143 offset:23136
	s_waitcnt vmcnt(11)
	ds_write_b128 v142, v[64:67] offset:46080
	global_load_dwordx4 v[64:67], v[188:189], off
	s_waitcnt lgkmcnt(5)
	v_mfma_f32_32x32x16_bf16 v[32:47], v[154:157], v[150:153], v[32:47]
	ds_write_b128 v142, v[72:75] offset:59904
	global_load_dwordx4 v[72:75], v[186:187], off
	v_mfma_f32_32x32x16_bf16 v[16:31], v[146:149], v[158:161], v[16:31]
	ds_write_b128 v142, v[76:79] offset:41472
	global_load_dwordx4 v[76:79], v[184:185], off
	v_mfma_f32_32x32x16_bf16 v[0:15], v[146:149], v[150:153], v[0:15]
	s_waitcnt vmcnt(11)
	ds_write_b128 v145, v[104:107] offset:13824
	global_load_dwordx4 v[104:107], v[194:195], off
	s_waitcnt lgkmcnt(6)
	v_mfma_f32_32x32x16_bf16 v[48:63], v[162:165], v[166:169], v[48:63]
	ds_write_b128 v142, v[84:87] offset:50688
	global_load_dwordx4 v[84:87], v[192:193], off
	s_waitcnt lgkmcnt(5)
	v_mfma_f32_32x32x16_bf16 v[32:47], v[162:165], v[178:181], v[32:47]
	ds_write_b128 v142, v[88:91] offset:64512
	global_load_dwordx4 v[88:91], v[190:191], off
	v_mfma_f32_32x32x16_bf16 v[16:31], v[170:173], v[166:169], v[16:31]
	ds_write_b128 v142, v[68:71] offset:36864
	global_load_dwordx4 v[68:71], v[174:175], off
	v_mfma_f32_32x32x16_bf16 v[0:15], v[170:173], v[178:181], v[0:15]
	ds_write_b128 v142, v[80:83] offset:55296
	global_load_dwordx4 v[80:83], v[182:183], off
	s_setprio 0
	s_waitcnt lgkmcnt(0)
	s_barrier
	s_setprio 1
	ds_read_b128 v[146:149], v128 offset:36864
	ds_read_b128 v[154:157], v143 offset:59904
	ds_read_b128 v[150:153], v128 offset:41472
	ds_read_b128 v[158:161], v128 offset:36896
	s_add_i32 s14, s40, 0x100
	s_cmpk_lt_u32 s40, 0x300
	s_cselect_b32 s14, s14, 0x3c0
	s_lshl_b64 s[42:43], s[14:15], 1
	s_waitcnt lgkmcnt(2)
	v_mfma_f32_32x32x16_bf16 v[32:47], v[146:149], v[154:157], v[32:47]
	ds_read_b128 v[162:165], v143 offset:55296
	v_lshl_add_u64 v[166:167], v[130:131], 0, s[42:43]
	v_lshl_add_u64 v[168:169], v[132:133], 0, s[42:43]
	v_lshl_add_u64 v[174:175], v[166:167], 0, v[134:135]
	v_lshl_add_u64 v[182:183], v[168:169], 0, v[134:135]
	v_lshl_add_u64 v[184:185], v[166:167], 0, v[136:137]
	v_lshl_add_u64 v[186:187], v[168:169], 0, v[136:137]
	v_lshl_add_u64 v[188:189], v[166:167], 0, v[138:139]
	v_lshl_add_u64 v[190:191], v[168:169], 0, v[138:139]
	v_lshl_add_u64 v[192:193], v[166:167], 0, v[140:141]
	s_waitcnt lgkmcnt(0)
	v_mfma_f32_32x32x16_bf16 v[48:63], v[146:149], v[162:165], v[48:63]
	ds_read_b128 v[146:149], v143 offset:55328
	v_lshl_add_u64 v[194:195], v[168:169], 0, v[140:141]
	v_mfma_f32_32x32x16_bf16 v[16:31], v[150:153], v[162:165], v[16:31]
	ds_read_b128 v[162:165], v128 offset:41504
	v_mfma_f32_32x32x16_bf16 v[0:15], v[150:153], v[154:157], v[0:15]
	ds_read_b128 v[150:153], v143 offset:59936
	s_waitcnt lgkmcnt(2)
	v_mfma_f32_32x32x16_bf16 v[48:63], v[158:161], v[146:149], v[48:63]
	ds_read_b128 v[154:157], v128 offset:36928
	s_waitcnt lgkmcnt(1)
	v_mfma_f32_32x32x16_bf16 v[32:47], v[158:161], v[150:153], v[32:47]
	ds_read_b128 v[158:161], v143 offset:55360
	v_mfma_f32_32x32x16_bf16 v[16:31], v[162:165], v[146:149], v[16:31]
	ds_read_b128 v[146:149], v128 offset:41536
	v_mfma_f32_32x32x16_bf16 v[0:15], v[162:165], v[150:153], v[0:15]
	ds_read_b128 v[150:153], v143 offset:59968
	s_waitcnt lgkmcnt(2)
	v_mfma_f32_32x32x16_bf16 v[48:63], v[154:157], v[158:161], v[48:63]
	ds_read_b128 v[162:165], v128 offset:36960
	ds_read_b128 v[166:169], v143 offset:55392
	ds_read_b128 v[170:173], v128 offset:41568
	ds_read_b128 v[178:181], v143 offset:60000
	s_waitcnt vmcnt(11)
	ds_write_b128 v142, v[92:95] offset:9216
	global_load_dwordx4 v[92:95], v[188:189], off
	s_waitcnt lgkmcnt(5)
	v_mfma_f32_32x32x16_bf16 v[32:47], v[154:157], v[150:153], v[32:47]
	ds_write_b128 v142, v[100:103] offset:23040
	global_load_dwordx4 v[100:103], v[186:187], off
	v_mfma_f32_32x32x16_bf16 v[16:31], v[146:149], v[158:161], v[16:31]
	ds_write_b128 v142, v[108:111] offset:4608
	global_load_dwordx4 v[108:111], v[184:185], off
	v_mfma_f32_32x32x16_bf16 v[0:15], v[146:149], v[150:153], v[0:15]
	s_waitcnt vmcnt(11)
	ds_write_b128 v142, v[124:127] offset:32256
	global_load_dwordx4 v[124:127], v[194:195], off
	s_waitcnt lgkmcnt(6)
	v_mfma_f32_32x32x16_bf16 v[48:63], v[162:165], v[166:169], v[48:63]
	ds_write_b128 v142, v[116:119] offset:13824
	global_load_dwordx4 v[116:119], v[192:193], off
	s_waitcnt lgkmcnt(5)
	v_mfma_f32_32x32x16_bf16 v[32:47], v[162:165], v[178:181], v[32:47]
	ds_write_b128 v142, v[120:123] offset:27648
	global_load_dwordx4 v[120:123], v[190:191], off
	v_mfma_f32_32x32x16_bf16 v[16:31], v[170:173], v[166:169], v[16:31]
	ds_write_b128 v142, v[96:99]
	global_load_dwordx4 v[96:99], v[174:175], off
	v_mfma_f32_32x32x16_bf16 v[0:15], v[170:173], v[178:181], v[0:15]
	ds_write_b128 v142, v[112:115] offset:18432
	global_load_dwordx4 v[112:115], v[182:183], off
	s_setprio 0
	s_add_i32 s14, s40, 0x80
	s_cmpk_lt_u32 s40, 0x380
	s_mov_b32 s40, s14
	s_waitcnt lgkmcnt(0)
	s_barrier
	s_cbranch_scc1 .LBB0_631
	s_addk_i32 s53, 0xe000
	s_lshr_b32 s14, s53, 12
	s_mulk_i32 s14, 0xc00
	s_barrier
	s_addk_i32 s14, 0xc00
	s_waitcnt vmcnt(15)
	v_lshrrev_b32_e32 v64, 6, v144
	s_waitcnt vmcnt(9)
	v_mul_lo_u32 v68, v64, s50
	v_lshrrev_b32_e32 v64, 3, v144
	s_and_b64 s[34:35], s[34:35], exec
	v_and_b32_e32 v64, 4, v64
	s_cselect_b32 s14, 0, s14
	v_cvt_pk_bf16_f32 v48, v48, v49
	v_cvt_pk_bf16_f32 v49, v50, v51
	v_mul_u32_u24_e32 v50, 0x48, v64
	s_lshl_b64 s[34:35], s[14:15], 2
	v_lshlrev_b32_e32 v65, 1, v144
	v_lshl_add_u32 v50, v50, 1, v68
	s_add_u32 s40, s12, s34
	v_and_or_b32 v69, v65, 62, v50
	s_addc_u32 s41, s13, s35
	s_lshl_b64 s[34:35], s[38:39], 1
	ds_write_b16 v69, v48
	ds_write_b16_d16_hi v69, v48 offset:144
	ds_write_b16 v69, v49 offset:288
	ds_write_b16_d16_hi v69, v49 offset:432
	v_cvt_pk_bf16_f32 v48, v52, v53
	v_cvt_pk_bf16_f32 v49, v54, v55
	s_add_u32 s14, s47, s34
	ds_write_b16 v69, v48 offset:1152
	ds_write_b16_d16_hi v69, v48 offset:1296
	ds_write_b16 v69, v49 offset:1440
	ds_write_b16_d16_hi v69, v49 offset:1584
	v_cvt_pk_bf16_f32 v48, v56, v57
	v_cvt_pk_bf16_f32 v49, v58, v59
	s_addc_u32 s38, s48, s35
	s_lshl_b32 s39, s54, 2
	ds_write_b16 v69, v48 offset:2304
	ds_write_b16_d16_hi v69, v48 offset:2448
	ds_write_b16 v69, v49 offset:2592
	ds_write_b16_d16_hi v69, v49 offset:2736
	v_cvt_pk_bf16_f32 v48, v60, v61
	v_cvt_pk_bf16_f32 v49, v62, v63
	v_cvt_pk_bf16_f32 v32, v32, v33
	s_add_u32 s34, s36, s39
	ds_write_b16 v69, v48 offset:3456
	ds_write_b16_d16_hi v69, v48 offset:3600
	ds_write_b16 v69, v49 offset:3744
	ds_write_b16_d16_hi v69, v49 offset:3888
	v_cvt_pk_bf16_f32 v49, v34, v35
	ds_write_b16 v69, v32 offset:64
	ds_write_b16_d16_hi v69, v32 offset:208
	ds_write_b16 v69, v49 offset:352
	v_lshlrev_b32_e32 v32, 3, v144
	s_addc_u32 s35, s37, 0
	v_and_b32_e32 v70, 56, v32
	s_add_u32 s36, s40, s39
	v_and_or_b32 v48, v144, 64, v70
	s_addc_u32 s37, s41, 0
	v_ashrrev_i32_e32 v32, 1, v144
	v_lshlrev_b32_e32 v128, 2, v48
	v_bfe_u32 v71, v144, 3, 3
	v_lshl_add_u64 v[62:63], s[36:37], 0, v[128:129]
	v_and_or_b32 v32, v32, s51, v71
	v_ashrrev_i32_e32 v33, 31, v32
	v_add_co_u32_e32 v34, vcc, s3, v62
	v_lshlrev_b64 v[66:67], 10, v[32:33]
	s_nop 0
	v_addc_co_u32_e32 v35, vcc, 0, v63, vcc
	global_load_dwordx4 v[50:53], v[34:35], off
	v_or_b32_e32 v66, v66, v48
	v_lshl_add_u64 v[64:65], v[66:67], 2, s[34:35]
	global_load_dwordx4 v[54:57], v[64:65], off offset:16
	global_load_dwordx4 v[58:61], v[64:65], off
	v_cvt_pk_bf16_f32 v33, v36, v37
	ds_write_b16_d16_hi v69, v49 offset:496
	v_cvt_pk_bf16_f32 v38, v38, v39
	ds_write_b16 v69, v33 offset:1216
	ds_write_b16_d16_hi v69, v33 offset:1360
	ds_write_b16 v69, v38 offset:1504
	v_lshl_add_u64 v[36:37], v[62:63], 0, s[28:29]
	global_load_dwordx4 v[62:65], v[36:37], off offset:16
	v_or_b32_e32 v130, 8, v32
	v_lshl_or_b32 v130, v130, 10, v48
	v_lshlrev_b32_e32 v130, 2, v130
	global_load_dwordx4 v[72:75], v130, s[34:35]
	global_load_dwordx4 v[76:79], v130, s[34:35] offset:16
	v_or_b32_e32 v130, 16, v32
	v_lshl_or_b32 v130, v130, 10, v48
	v_lshlrev_b32_e32 v130, 2, v130
	global_load_dwordx4 v[80:83], v130, s[34:35]
	global_load_dwordx4 v[84:87], v130, s[34:35] offset:16
	v_or_b32_e32 v130, 24, v32
	v_lshl_or_b32 v130, v130, 10, v48
	v_lshlrev_b32_e32 v130, 2, v130
	global_load_dwordx4 v[88:91], v130, s[34:35]
	global_load_dwordx4 v[92:95], v130, s[34:35] offset:16
	v_or_b32_e32 v130, 32, v32
	v_lshl_or_b32 v130, v130, 10, v48
	v_lshlrev_b32_e32 v130, 2, v130
	global_load_dwordx4 v[96:99], v130, s[34:35]
	global_load_dwordx4 v[100:103], v130, s[34:35] offset:16
	v_or_b32_e32 v130, 40, v32
	v_lshl_or_b32 v130, v130, 10, v48
	v_lshlrev_b32_e32 v130, 2, v130
	global_load_dwordx4 v[104:107], v130, s[34:35]
	global_load_dwordx4 v[108:111], v130, s[34:35] offset:16
	v_or_b32_e32 v130, 48, v32
	v_lshl_or_b32 v130, v130, 10, v48
	v_lshlrev_b32_e32 v130, 2, v130
	global_load_dwordx4 v[112:115], v130, s[34:35]
	global_load_dwordx4 v[116:119], v130, s[34:35] offset:16
	v_or_b32_e32 v130, 56, v32
	v_lshl_or_b32 v130, v130, 10, v48
	v_lshlrev_b32_e32 v130, 2, v130
	global_load_dwordx4 v[120:123], v130, s[34:35]
	global_load_dwordx4 v[124:127], v130, s[34:35] offset:16
	v_cvt_pk_bf16_f32 v33, v40, v41
	ds_write_b16_d16_hi v69, v38 offset:1648
	v_cvt_pk_bf16_f32 v38, v42, v43
	ds_write_b16 v69, v33 offset:2368
	ds_write_b16_d16_hi v69, v33 offset:2512
	ds_write_b16 v69, v38 offset:2656
	ds_write_b16_d16_hi v69, v38 offset:2800
	v_cvt_pk_bf16_f32 v33, v44, v45
	v_cvt_pk_bf16_f32 v16, v16, v17
	v_cvt_pk_bf16_f32 v38, v46, v47
	ds_write_b16 v69, v33 offset:3520
	ds_write_b16_d16_hi v69, v33 offset:3664
	ds_write_b16 v69, v38 offset:3808
	ds_write_b16_d16_hi v69, v38 offset:3952
	v_cvt_pk_bf16_f32 v17, v18, v19
	ds_write_b16 v69, v16 offset:4608
	ds_write_b16_d16_hi v69, v16 offset:4752
	ds_write_b16 v69, v17 offset:4896
	ds_write_b16_d16_hi v69, v17 offset:5040
	v_cvt_pk_bf16_f32 v16, v20, v21
	v_cvt_pk_bf16_f32 v17, v22, v23
	ds_write_b16 v69, v16 offset:5760
	ds_write_b16_d16_hi v69, v16 offset:5904
	ds_write_b16 v69, v17 offset:6048
	ds_write_b16_d16_hi v69, v17 offset:6192
	v_cvt_pk_bf16_f32 v16, v24, v25
	v_cvt_pk_bf16_f32 v17, v26, v27
	ds_write_b16 v69, v16 offset:6912
	ds_write_b16_d16_hi v69, v16 offset:7056
	ds_write_b16 v69, v17 offset:7200
	ds_write_b16_d16_hi v69, v17 offset:7344
	v_cvt_pk_bf16_f32 v16, v28, v29
	v_cvt_pk_bf16_f32 v0, v0, v1
	v_cvt_pk_bf16_f32 v17, v30, v31
	ds_write_b16 v69, v16 offset:8064
	ds_write_b16_d16_hi v69, v16 offset:8208
	ds_write_b16 v69, v17 offset:8352
	ds_write_b16_d16_hi v69, v17 offset:8496
	v_cvt_pk_bf16_f32 v1, v2, v3
	ds_write_b16 v69, v0 offset:4672
	ds_write_b16_d16_hi v69, v0 offset:4816
	ds_write_b16 v69, v1 offset:4960
	ds_write_b16_d16_hi v69, v1 offset:5104
	v_cvt_pk_bf16_f32 v0, v4, v5
	v_cvt_pk_bf16_f32 v1, v6, v7
	ds_write_b16 v69, v0 offset:5824
	ds_write_b16_d16_hi v69, v0 offset:5968
	ds_write_b16 v69, v1 offset:6112
	ds_write_b16_d16_hi v69, v1 offset:6256
	v_cvt_pk_bf16_f32 v0, v8, v9
	v_cvt_pk_bf16_f32 v1, v10, v11
	ds_write_b16 v69, v0 offset:6976
	ds_write_b16_d16_hi v69, v0 offset:7120
	ds_write_b16 v69, v1 offset:7264
	ds_write_b16_d16_hi v69, v1 offset:7408
	v_cvt_pk_bf16_f32 v0, v12, v13
	v_cvt_pk_bf16_f32 v1, v14, v15
	ds_write_b16 v69, v0 offset:8128
	ds_write_b16_d16_hi v69, v0 offset:8272
	ds_write_b16 v69, v1 offset:8416
	ds_write_b16_d16_hi v69, v1 offset:8560
	v_lshl_or_b32 v0, v70, 1, v68
	v_mad_u32_u24 v0, v71, s49, v0
	ds_read_b128 v[2:5], v0
	s_lshl_b32 s39, s54, 1
	s_add_u32 s36, s14, s39
	s_addc_u32 s37, s38, 0
	ds_read_b128 v[6:9], v0 offset:1152
	s_waitcnt lgkmcnt(1)
	v_lshlrev_b32_e32 v12, 16, v2
	v_and_b32_e32 v13, 0xffff0000, v2
	s_waitcnt vmcnt(14)
	v_pk_add_f32 v[10:11], v[50:51], 1.0 op_sel_hi:[1,0]
	s_nop 0
	v_pk_mul_f32 v[10:11], v[10:11], v[12:13]
	v_lshlrev_b32_e32 v12, 16, v3
	v_pk_fma_f32 v[10:11], v[58:59], s[30:31], v[10:11] op_sel_hi:[1,0,1]
	v_and_b32_e32 v13, 0xffff0000, v3
	v_cvt_pk_bf16_f32 v2, v10, v11
	v_pk_add_f32 v[10:11], v[52:53], 1.0 op_sel_hi:[1,0]
	s_nop 0
	v_pk_mul_f32 v[10:11], v[10:11], v[12:13]
	v_lshlrev_b32_e32 v12, 16, v4
	v_pk_fma_f32 v[10:11], v[60:61], s[30:31], v[10:11] op_sel_hi:[1,0,1]
	v_and_b32_e32 v13, 0xffff0000, v4
	v_cvt_pk_bf16_f32 v3, v10, v11
	v_pk_add_f32 v[10:11], v[62:63], 1.0 op_sel_hi:[1,0]
	s_nop 0
	v_pk_mul_f32 v[10:11], v[10:11], v[12:13]
	v_lshlrev_b32_e32 v12, 16, v5
	v_pk_fma_f32 v[10:11], v[54:55], s[30:31], v[10:11] op_sel_hi:[1,0,1]
	v_and_b32_e32 v13, 0xffff0000, v5
	v_cvt_pk_bf16_f32 v4, v10, v11
	v_pk_add_f32 v[10:11], v[64:65], 1.0 op_sel_hi:[1,0]
	s_nop 0
	v_pk_mul_f32 v[10:11], v[10:11], v[12:13]
	s_nop 0
	v_pk_fma_f32 v[10:11], v[56:57], s[30:31], v[10:11] op_sel_hi:[1,0,1]
	s_nop 0
	v_cvt_pk_bf16_f32 v5, v10, v11
	v_lshl_add_u64 v[10:11], v[66:67], 1, s[36:37]
	s_waitcnt vmcnt(0)
	global_store_dwordx4 v[10:11], v[2:5], off
	v_or_b32_e32 v10, 8, v32
	v_ashrrev_i32_e32 v11, 31, v10
	v_lshlrev_b64 v[22:23], 10, v[10:11]
	v_or_b32_e32 v22, v22, v48
	v_lshl_add_u64 v[24:25], v[22:23], 2, s[34:35]
	s_waitcnt lgkmcnt(0)
	v_lshlrev_b32_e32 v24, 16, v6
	v_and_b32_e32 v25, 0xffff0000, v6
	v_lshlrev_b32_e32 v6, 16, v7
	v_and_b32_e32 v7, 0xffff0000, v7
	v_pk_add_f32 v[2:3], v[50:51], 1.0 op_sel_hi:[1,0]
	v_pk_add_f32 v[4:5], v[52:53], 1.0 op_sel_hi:[1,0]
	v_pk_mul_f32 v[2:3], v[2:3], v[24:25]
	v_pk_mul_f32 v[4:5], v[4:5], v[6:7]
	v_pk_fma_f32 v[2:3], v[72:73], s[30:31], v[2:3] op_sel_hi:[1,0,1]
	v_pk_fma_f32 v[4:5], v[74:75], s[30:31], v[4:5] op_sel_hi:[1,0,1]
	v_cvt_pk_bf16_f32 v2, v2, v3
	v_cvt_pk_bf16_f32 v3, v4, v5
	v_pk_add_f32 v[4:5], v[62:63], 1.0 op_sel_hi:[1,0]
	v_lshlrev_b32_e32 v6, 16, v8
	v_and_b32_e32 v7, 0xffff0000, v8
	v_pk_mul_f32 v[4:5], v[4:5], v[6:7]
	v_pk_add_f32 v[6:7], v[64:65], 1.0 op_sel_hi:[1,0]
	v_lshlrev_b32_e32 v8, 16, v9
	v_and_b32_e32 v9, 0xffff0000, v9
	v_pk_mul_f32 v[6:7], v[6:7], v[8:9]
	v_pk_fma_f32 v[4:5], v[76:77], s[30:31], v[4:5] op_sel_hi:[1,0,1]
	v_pk_fma_f32 v[6:7], v[78:79], s[30:31], v[6:7] op_sel_hi:[1,0,1]
	v_or_b32_e32 v10, 16, v32
	v_cvt_pk_bf16_f32 v4, v4, v5
	v_cvt_pk_bf16_f32 v5, v6, v7
	v_lshl_add_u64 v[6:7], v[22:23], 1, s[36:37]
	v_ashrrev_i32_e32 v11, 31, v10
	global_store_dwordx4 v[6:7], v[2:5], off
	v_lshlrev_b64 v[26:27], 10, v[10:11]
	v_or_b32_e32 v26, v26, v48
	v_lshl_add_u64 v[18:19], v[26:27], 2, s[34:35]
	ds_read_b128 v[18:21], v0 offset:2304
	ds_read_b128 v[22:25], v0 offset:3456
	v_lshl_add_u64 v[26:27], v[26:27], 1, s[36:37]
	s_waitcnt lgkmcnt(1)
	v_lshlrev_b32_e32 v28, 16, v18
	v_and_b32_e32 v29, 0xffff0000, v18
	v_lshlrev_b32_e32 v18, 16, v19
	v_and_b32_e32 v19, 0xffff0000, v19
	v_lshlrev_b32_e32 v30, 16, v20
	v_and_b32_e32 v31, 0xffff0000, v20
	v_lshlrev_b32_e32 v20, 16, v21
	v_and_b32_e32 v21, 0xffff0000, v21
	v_pk_add_f32 v[2:3], v[50:51], 1.0 op_sel_hi:[1,0]
	v_pk_add_f32 v[4:5], v[52:53], 1.0 op_sel_hi:[1,0]
	v_pk_add_f32 v[6:7], v[62:63], 1.0 op_sel_hi:[1,0]
	v_pk_add_f32 v[8:9], v[64:65], 1.0 op_sel_hi:[1,0]
	v_pk_mul_f32 v[2:3], v[2:3], v[28:29]
	v_pk_mul_f32 v[4:5], v[4:5], v[18:19]
	v_pk_mul_f32 v[6:7], v[6:7], v[30:31]
	v_pk_mul_f32 v[8:9], v[8:9], v[20:21]
	v_pk_fma_f32 v[2:3], v[80:81], s[30:31], v[2:3] op_sel_hi:[1,0,1]
	v_pk_fma_f32 v[4:5], v[82:83], s[30:31], v[4:5] op_sel_hi:[1,0,1]
	v_pk_fma_f32 v[6:7], v[84:85], s[30:31], v[6:7] op_sel_hi:[1,0,1]
	v_pk_fma_f32 v[8:9], v[86:87], s[30:31], v[8:9] op_sel_hi:[1,0,1]
	v_or_b32_e32 v10, 24, v32
	v_cvt_pk_bf16_f32 v2, v2, v3
	v_cvt_pk_bf16_f32 v3, v4, v5
	v_cvt_pk_bf16_f32 v4, v6, v7
	v_cvt_pk_bf16_f32 v5, v8, v9
	v_ashrrev_i32_e32 v11, 31, v10
	global_store_dwordx4 v[26:27], v[2:5], off
	v_lshlrev_b64 v[18:19], 10, v[10:11]
	v_or_b32_e32 v18, v18, v48
	v_lshl_add_u64 v[20:21], v[18:19], 2, s[34:35]
	s_waitcnt lgkmcnt(0)
	v_lshlrev_b32_e32 v20, 16, v22
	v_and_b32_e32 v21, 0xffff0000, v22
	v_lshlrev_b32_e32 v22, 16, v23
	v_and_b32_e32 v23, 0xffff0000, v23
	v_lshlrev_b32_e32 v26, 16, v24
	v_and_b32_e32 v27, 0xffff0000, v24
	v_lshlrev_b32_e32 v24, 16, v25
	v_and_b32_e32 v25, 0xffff0000, v25
	v_lshl_add_u64 v[18:19], v[18:19], 1, s[36:37]
	v_pk_add_f32 v[2:3], v[50:51], 1.0 op_sel_hi:[1,0]
	v_pk_add_f32 v[4:5], v[52:53], 1.0 op_sel_hi:[1,0]
	v_pk_add_f32 v[6:7], v[62:63], 1.0 op_sel_hi:[1,0]
	v_pk_add_f32 v[8:9], v[64:65], 1.0 op_sel_hi:[1,0]
	v_pk_mul_f32 v[2:3], v[2:3], v[20:21]
	v_pk_mul_f32 v[4:5], v[4:5], v[22:23]
	v_pk_mul_f32 v[6:7], v[6:7], v[26:27]
	v_pk_mul_f32 v[8:9], v[8:9], v[24:25]
	v_pk_fma_f32 v[2:3], v[88:89], s[30:31], v[2:3] op_sel_hi:[1,0,1]
	v_pk_fma_f32 v[4:5], v[90:91], s[30:31], v[4:5] op_sel_hi:[1,0,1]
	v_pk_fma_f32 v[6:7], v[92:93], s[30:31], v[6:7] op_sel_hi:[1,0,1]
	v_pk_fma_f32 v[8:9], v[94:95], s[30:31], v[8:9] op_sel_hi:[1,0,1]
	v_or_b32_e32 v10, 32, v32
	v_cvt_pk_bf16_f32 v2, v2, v3
	v_cvt_pk_bf16_f32 v3, v4, v5
	v_cvt_pk_bf16_f32 v4, v6, v7
	v_cvt_pk_bf16_f32 v5, v8, v9
	v_ashrrev_i32_e32 v11, 31, v10
	global_store_dwordx4 v[18:19], v[2:5], off
	v_lshlrev_b64 v[26:27], 10, v[10:11]
	v_or_b32_e32 v26, v26, v48
	v_lshl_add_u64 v[18:19], v[26:27], 2, s[34:35]
	ds_read_b128 v[18:21], v0 offset:4608
	ds_read_b128 v[22:25], v0 offset:5760
	v_lshl_add_u64 v[26:27], v[26:27], 1, s[36:37]
	s_waitcnt lgkmcnt(1)
	v_lshlrev_b32_e32 v28, 16, v18
	v_and_b32_e32 v29, 0xffff0000, v18
	v_lshlrev_b32_e32 v18, 16, v19
	v_and_b32_e32 v19, 0xffff0000, v19
	v_lshlrev_b32_e32 v30, 16, v20
	v_and_b32_e32 v31, 0xffff0000, v20
	v_lshlrev_b32_e32 v20, 16, v21
	v_and_b32_e32 v21, 0xffff0000, v21
	v_pk_add_f32 v[2:3], v[50:51], 1.0 op_sel_hi:[1,0]
	v_pk_add_f32 v[4:5], v[52:53], 1.0 op_sel_hi:[1,0]
	v_pk_add_f32 v[6:7], v[62:63], 1.0 op_sel_hi:[1,0]
	v_pk_add_f32 v[8:9], v[64:65], 1.0 op_sel_hi:[1,0]
	v_pk_mul_f32 v[2:3], v[2:3], v[28:29]
	v_pk_mul_f32 v[4:5], v[4:5], v[18:19]
	v_pk_mul_f32 v[6:7], v[6:7], v[30:31]
	v_pk_mul_f32 v[8:9], v[8:9], v[20:21]
	v_pk_fma_f32 v[2:3], v[96:97], s[30:31], v[2:3] op_sel_hi:[1,0,1]
	v_pk_fma_f32 v[4:5], v[98:99], s[30:31], v[4:5] op_sel_hi:[1,0,1]
	v_pk_fma_f32 v[6:7], v[100:101], s[30:31], v[6:7] op_sel_hi:[1,0,1]
	v_pk_fma_f32 v[8:9], v[102:103], s[30:31], v[8:9] op_sel_hi:[1,0,1]
	v_or_b32_e32 v10, 40, v32
	v_cvt_pk_bf16_f32 v2, v2, v3
	v_cvt_pk_bf16_f32 v3, v4, v5
	v_cvt_pk_bf16_f32 v4, v6, v7
	v_cvt_pk_bf16_f32 v5, v8, v9
	v_ashrrev_i32_e32 v11, 31, v10
	global_store_dwordx4 v[26:27], v[2:5], off
	v_lshlrev_b64 v[18:19], 10, v[10:11]
	v_or_b32_e32 v18, v18, v48
	v_lshl_add_u64 v[20:21], v[18:19], 2, s[34:35]
	s_waitcnt lgkmcnt(0)
	v_lshlrev_b32_e32 v20, 16, v22
	v_and_b32_e32 v21, 0xffff0000, v22
	v_lshlrev_b32_e32 v22, 16, v23
	v_and_b32_e32 v23, 0xffff0000, v23
	v_lshlrev_b32_e32 v26, 16, v24
	v_and_b32_e32 v27, 0xffff0000, v24
	v_lshlrev_b32_e32 v24, 16, v25
	v_and_b32_e32 v25, 0xffff0000, v25
	v_lshl_add_u64 v[18:19], v[18:19], 1, s[36:37]
	v_pk_add_f32 v[2:3], v[50:51], 1.0 op_sel_hi:[1,0]
	v_pk_add_f32 v[4:5], v[52:53], 1.0 op_sel_hi:[1,0]
	v_pk_add_f32 v[6:7], v[62:63], 1.0 op_sel_hi:[1,0]
	v_pk_add_f32 v[8:9], v[64:65], 1.0 op_sel_hi:[1,0]
	v_pk_mul_f32 v[2:3], v[2:3], v[20:21]
	v_pk_mul_f32 v[4:5], v[4:5], v[22:23]
	v_pk_mul_f32 v[6:7], v[6:7], v[26:27]
	v_pk_mul_f32 v[8:9], v[8:9], v[24:25]
	v_pk_fma_f32 v[2:3], v[104:105], s[30:31], v[2:3] op_sel_hi:[1,0,1]
	v_pk_fma_f32 v[4:5], v[106:107], s[30:31], v[4:5] op_sel_hi:[1,0,1]
	v_pk_fma_f32 v[6:7], v[108:109], s[30:31], v[6:7] op_sel_hi:[1,0,1]
	v_pk_fma_f32 v[8:9], v[110:111], s[30:31], v[8:9] op_sel_hi:[1,0,1]
	v_or_b32_e32 v10, 48, v32
	v_cvt_pk_bf16_f32 v2, v2, v3
	v_cvt_pk_bf16_f32 v3, v4, v5
	v_cvt_pk_bf16_f32 v4, v6, v7
	v_cvt_pk_bf16_f32 v5, v8, v9
	v_ashrrev_i32_e32 v11, 31, v10
	global_store_dwordx4 v[18:19], v[2:5], off
	v_lshlrev_b64 v[26:27], 10, v[10:11]
	v_or_b32_e32 v26, v26, v48
	v_lshl_add_u64 v[18:19], v[26:27], 2, s[34:35]
	ds_read_b128 v[18:21], v0 offset:6912
	ds_read_b128 v[22:25], v0 offset:8064
	v_lshl_add_u64 v[26:27], v[26:27], 1, s[36:37]
	s_waitcnt lgkmcnt(1)
	v_lshlrev_b32_e32 v0, 16, v18
	v_and_b32_e32 v1, 0xffff0000, v18
	v_lshlrev_b32_e32 v18, 16, v19
	v_and_b32_e32 v19, 0xffff0000, v19
	v_lshlrev_b32_e32 v28, 16, v20
	v_and_b32_e32 v29, 0xffff0000, v20
	v_lshlrev_b32_e32 v20, 16, v21
	v_and_b32_e32 v21, 0xffff0000, v21
	v_pk_add_f32 v[2:3], v[50:51], 1.0 op_sel_hi:[1,0]
	v_pk_add_f32 v[4:5], v[52:53], 1.0 op_sel_hi:[1,0]
	v_pk_add_f32 v[6:7], v[62:63], 1.0 op_sel_hi:[1,0]
	v_pk_add_f32 v[8:9], v[64:65], 1.0 op_sel_hi:[1,0]
	v_pk_mul_f32 v[0:1], v[2:3], v[0:1]
	v_pk_mul_f32 v[2:3], v[4:5], v[18:19]
	v_pk_mul_f32 v[4:5], v[6:7], v[28:29]
	v_pk_mul_f32 v[6:7], v[8:9], v[20:21]
	v_pk_fma_f32 v[0:1], v[112:113], s[30:31], v[0:1] op_sel_hi:[1,0,1]
	v_pk_fma_f32 v[2:3], v[114:115], s[30:31], v[2:3] op_sel_hi:[1,0,1]
	v_pk_fma_f32 v[4:5], v[116:117], s[30:31], v[4:5] op_sel_hi:[1,0,1]
	v_pk_fma_f32 v[6:7], v[118:119], s[30:31], v[6:7] op_sel_hi:[1,0,1]
	v_or_b32_e32 v8, 56, v32
	v_cvt_pk_bf16_f32 v0, v0, v1
	v_cvt_pk_bf16_f32 v1, v2, v3
	v_cvt_pk_bf16_f32 v2, v4, v5
	v_cvt_pk_bf16_f32 v3, v6, v7
	v_ashrrev_i32_e32 v9, 31, v8
	global_store_dwordx4 v[26:27], v[0:3], off
	v_lshlrev_b64 v[16:17], 10, v[8:9]
	v_or_b32_e32 v16, v16, v48
	v_lshl_add_u64 v[18:19], v[16:17], 2, s[34:35]
	s_waitcnt lgkmcnt(0)
	v_lshlrev_b32_e32 v18, 16, v22
	v_and_b32_e32 v19, 0xffff0000, v22
	v_lshlrev_b32_e32 v20, 16, v23
	v_and_b32_e32 v21, 0xffff0000, v23
	v_lshlrev_b32_e32 v22, 16, v24
	v_and_b32_e32 v23, 0xffff0000, v24
	v_lshlrev_b32_e32 v24, 16, v25
	v_and_b32_e32 v25, 0xffff0000, v25
	v_pk_add_f32 v[0:1], v[50:51], 1.0 op_sel_hi:[1,0]
	v_pk_add_f32 v[2:3], v[52:53], 1.0 op_sel_hi:[1,0]
	v_pk_add_f32 v[4:5], v[62:63], 1.0 op_sel_hi:[1,0]
	v_pk_add_f32 v[6:7], v[64:65], 1.0 op_sel_hi:[1,0]
	v_pk_mul_f32 v[0:1], v[0:1], v[18:19]
	v_pk_mul_f32 v[2:3], v[2:3], v[20:21]
	v_pk_mul_f32 v[4:5], v[4:5], v[22:23]
	v_pk_mul_f32 v[6:7], v[6:7], v[24:25]
	v_pk_fma_f32 v[0:1], v[120:121], s[30:31], v[0:1] op_sel_hi:[1,0,1]
	v_pk_fma_f32 v[2:3], v[122:123], s[30:31], v[2:3] op_sel_hi:[1,0,1]
	v_pk_fma_f32 v[4:5], v[124:125], s[30:31], v[4:5] op_sel_hi:[1,0,1]
	v_pk_fma_f32 v[6:7], v[126:127], s[30:31], v[6:7] op_sel_hi:[1,0,1]
	v_cvt_pk_bf16_f32 v0, v0, v1
	v_cvt_pk_bf16_f32 v1, v2, v3
	v_cvt_pk_bf16_f32 v2, v4, v5
	v_cvt_pk_bf16_f32 v3, v6, v7
	v_lshl_add_u64 v[4:5], v[16:17], 1, s[36:37]
	global_store_dwordx4 v[4:5], v[0:3], off
	s_load_dword s14, s[16:17], 0x0
	s_waitcnt lgkmcnt(0)
	s_add_i32 s52, s14, s52
	s_cmpk_lt_i32 s52, 0x400
	s_cbranch_scc1 .LBB0_626
	s_load_dword s3, s[0:1], 0x10c
	s_waitcnt lgkmcnt(0)
	v_mov_b32_e32 v10, s3

.LBB0_1466:
	s_setprio 1
	ds_read_b128 v[146:149], v128
	ds_read_b128 v[154:157], v143 offset:23040
	ds_read_b128 v[150:153], v128 offset:4608
	ds_read_b128 v[158:161], v128 offset:32
	s_add_i32 s12, s35, 0xc0
	s_cmpk_lt_u32 s35, 0x340
	s_cselect_b32 s12, s12, 0x3c0
	s_lshl_b64 s[36:37], s[12:13], 1
	s_waitcnt lgkmcnt(2)
	v_mfma_f32_32x32x16_bf16 v[32:47], v[146:149], v[154:157], v[32:47]
	ds_read_b128 v[162:165], v143 offset:18432
	v_lshl_add_u64 v[166:167], v[130:131], 0, s[36:37]
	v_lshl_add_u64 v[168:169], v[132:133], 0, s[36:37]
	v_lshl_add_u64 v[174:175], v[166:167], 0, v[134:135]
	v_lshl_add_u64 v[182:183], v[168:169], 0, v[134:135]
	v_lshl_add_u64 v[184:185], v[166:167], 0, v[136:137]
	v_lshl_add_u64 v[186:187], v[168:169], 0, v[136:137]
	v_lshl_add_u64 v[188:189], v[166:167], 0, v[138:139]
	v_lshl_add_u64 v[190:191], v[168:169], 0, v[138:139]
	v_lshl_add_u64 v[192:193], v[166:167], 0, v[140:141]
	s_waitcnt lgkmcnt(0)
	v_mfma_f32_32x32x16_bf16 v[48:63], v[146:149], v[162:165], v[48:63]
	ds_read_b128 v[146:149], v143 offset:18464
	v_lshl_add_u64 v[194:195], v[168:169], 0, v[140:141]
	v_mfma_f32_32x32x16_bf16 v[16:31], v[150:153], v[162:165], v[16:31]
	ds_read_b128 v[162:165], v128 offset:4640
	v_mfma_f32_32x32x16_bf16 v[0:15], v[150:153], v[154:157], v[0:15]
	ds_read_b128 v[150:153], v143 offset:23072
	s_waitcnt lgkmcnt(2)
	v_mfma_f32_32x32x16_bf16 v[48:63], v[158:161], v[146:149], v[48:63]
	ds_read_b128 v[154:157], v128 offset:64
	s_waitcnt lgkmcnt(1)
	v_mfma_f32_32x32x16_bf16 v[32:47], v[158:161], v[150:153], v[32:47]
	ds_read_b128 v[158:161], v143 offset:18496
	v_mfma_f32_32x32x16_bf16 v[16:31], v[162:165], v[146:149], v[16:31]
	ds_read_b128 v[146:149], v128 offset:4672
	v_mfma_f32_32x32x16_bf16 v[0:15], v[162:165], v[150:153], v[0:15]
	ds_read_b128 v[150:153], v143 offset:23104
	s_waitcnt lgkmcnt(2)
	v_mfma_f32_32x32x16_bf16 v[48:63], v[154:157], v[158:161], v[48:63]
	ds_read_b128 v[162:165], v128 offset:96
	ds_read_b128 v[166:169], v143 offset:18528
	ds_read_b128 v[170:173], v128 offset:4704
	ds_read_b128 v[178:181], v143 offset:23136
	s_waitcnt vmcnt(11)
	ds_write_b128 v142, v[64:67] offset:46080
	global_load_dwordx4 v[64:67], v[188:189], off
	s_waitcnt lgkmcnt(5)
	v_mfma_f32_32x32x16_bf16 v[32:47], v[154:157], v[150:153], v[32:47]
	ds_write_b128 v142, v[72:75] offset:59904
	global_load_dwordx4 v[72:75], v[186:187], off
	v_mfma_f32_32x32x16_bf16 v[16:31], v[146:149], v[158:161], v[16:31]
	ds_write_b128 v142, v[76:79] offset:41472
	global_load_dwordx4 v[76:79], v[184:185], off
	v_mfma_f32_32x32x16_bf16 v[0:15], v[146:149], v[150:153], v[0:15]
	s_waitcnt vmcnt(11)
	ds_write_b128 v145, v[104:107] offset:13824
	global_load_dwordx4 v[104:107], v[194:195], off
	s_waitcnt lgkmcnt(6)
	v_mfma_f32_32x32x16_bf16 v[48:63], v[162:165], v[166:169], v[48:63]
	ds_write_b128 v142, v[84:87] offset:50688
	global_load_dwordx4 v[84:87], v[192:193], off
	s_waitcnt lgkmcnt(5)
	v_mfma_f32_32x32x16_bf16 v[32:47], v[162:165], v[178:181], v[32:47]
	ds_write_b128 v142, v[88:91] offset:64512
	global_load_dwordx4 v[88:91], v[190:191], off
	v_mfma_f32_32x32x16_bf16 v[16:31], v[170:173], v[166:169], v[16:31]
	ds_write_b128 v142, v[68:71] offset:36864
	global_load_dwordx4 v[68:71], v[174:175], off
	v_mfma_f32_32x32x16_bf16 v[0:15], v[170:173], v[178:181], v[0:15]
	ds_write_b128 v142, v[80:83] offset:55296
	global_load_dwordx4 v[80:83], v[182:183], off
	s_setprio 0
	s_waitcnt lgkmcnt(0)
	s_barrier
	s_setprio 1
	ds_read_b128 v[146:149], v128 offset:36864
	ds_read_b128 v[154:157], v143 offset:59904
	ds_read_b128 v[150:153], v128 offset:41472
	ds_read_b128 v[158:161], v128 offset:36896
	s_add_i32 s12, s35, 0x100
	s_cmpk_lt_u32 s35, 0x300
	s_cselect_b32 s12, s12, 0x3c0
	s_lshl_b64 s[36:37], s[12:13], 1
	s_waitcnt lgkmcnt(2)
	v_mfma_f32_32x32x16_bf16 v[32:47], v[146:149], v[154:157], v[32:47]
	ds_read_b128 v[162:165], v143 offset:55296
	v_lshl_add_u64 v[166:167], v[130:131], 0, s[36:37]
	v_lshl_add_u64 v[168:169], v[132:133], 0, s[36:37]
	v_lshl_add_u64 v[174:175], v[166:167], 0, v[134:135]
	v_lshl_add_u64 v[182:183], v[168:169], 0, v[134:135]
	v_lshl_add_u64 v[184:185], v[166:167], 0, v[136:137]
	v_lshl_add_u64 v[186:187], v[168:169], 0, v[136:137]
	v_lshl_add_u64 v[188:189], v[166:167], 0, v[138:139]
	v_lshl_add_u64 v[190:191], v[168:169], 0, v[138:139]
	v_lshl_add_u64 v[192:193], v[166:167], 0, v[140:141]
	s_waitcnt lgkmcnt(0)
	v_mfma_f32_32x32x16_bf16 v[48:63], v[146:149], v[162:165], v[48:63]
	ds_read_b128 v[146:149], v143 offset:55328
	v_lshl_add_u64 v[194:195], v[168:169], 0, v[140:141]
	v_mfma_f32_32x32x16_bf16 v[16:31], v[150:153], v[162:165], v[16:31]
	ds_read_b128 v[162:165], v128 offset:41504
	v_mfma_f32_32x32x16_bf16 v[0:15], v[150:153], v[154:157], v[0:15]
	ds_read_b128 v[150:153], v143 offset:59936
	s_waitcnt lgkmcnt(2)
	v_mfma_f32_32x32x16_bf16 v[48:63], v[158:161], v[146:149], v[48:63]
	ds_read_b128 v[154:157], v128 offset:36928
	s_waitcnt lgkmcnt(1)
	v_mfma_f32_32x32x16_bf16 v[32:47], v[158:161], v[150:153], v[32:47]
	ds_read_b128 v[158:161], v143 offset:55360
	v_mfma_f32_32x32x16_bf16 v[16:31], v[162:165], v[146:149], v[16:31]
	ds_read_b128 v[146:149], v128 offset:41536
	v_mfma_f32_32x32x16_bf16 v[0:15], v[162:165], v[150:153], v[0:15]
	ds_read_b128 v[150:153], v143 offset:59968
	s_waitcnt lgkmcnt(2)
	v_mfma_f32_32x32x16_bf16 v[48:63], v[154:157], v[158:161], v[48:63]
	ds_read_b128 v[162:165], v128 offset:36960
	ds_read_b128 v[166:169], v143 offset:55392
	ds_read_b128 v[170:173], v128 offset:41568
	ds_read_b128 v[178:181], v143 offset:60000
	s_waitcnt vmcnt(11)
	ds_write_b128 v142, v[92:95] offset:9216
	global_load_dwordx4 v[92:95], v[188:189], off
	s_waitcnt lgkmcnt(5)
	v_mfma_f32_32x32x16_bf16 v[32:47], v[154:157], v[150:153], v[32:47]
	ds_write_b128 v142, v[100:103] offset:23040
	global_load_dwordx4 v[100:103], v[186:187], off
	v_mfma_f32_32x32x16_bf16 v[16:31], v[146:149], v[158:161], v[16:31]
	ds_write_b128 v142, v[108:111] offset:4608
	global_load_dwordx4 v[108:111], v[184:185], off
	v_mfma_f32_32x32x16_bf16 v[0:15], v[146:149], v[150:153], v[0:15]
	s_waitcnt vmcnt(11)
	ds_write_b128 v142, v[124:127] offset:32256
	global_load_dwordx4 v[124:127], v[194:195], off
	s_waitcnt lgkmcnt(6)
	v_mfma_f32_32x32x16_bf16 v[48:63], v[162:165], v[166:169], v[48:63]
	ds_write_b128 v142, v[116:119] offset:13824
	global_load_dwordx4 v[116:119], v[192:193], off
	s_waitcnt lgkmcnt(5)
	v_mfma_f32_32x32x16_bf16 v[32:47], v[162:165], v[178:181], v[32:47]
	ds_write_b128 v142, v[120:123] offset:27648
	global_load_dwordx4 v[120:123], v[190:191], off
	v_mfma_f32_32x32x16_bf16 v[16:31], v[170:173], v[166:169], v[16:31]
	ds_write_b128 v142, v[96:99]
	global_load_dwordx4 v[96:99], v[174:175], off
	v_mfma_f32_32x32x16_bf16 v[0:15], v[170:173], v[178:181], v[0:15]
	ds_write_b128 v142, v[112:115] offset:18432
	global_load_dwordx4 v[112:115], v[182:183], off
	s_setprio 0
	s_add_i32 s12, s35, 0x80
	s_cmpk_lt_u32 s35, 0x380
	s_mov_b32 s35, s12
	s_waitcnt lgkmcnt(0)
	s_barrier
	s_cbranch_scc1 .LBB0_1466
	s_addk_i32 s50, 0xe000
	s_lshr_b32 s12, s50, 12
	s_mulk_i32 s12, 0xc00
	s_addk_i32 s12, 0x3000
	s_cmpk_gt_i32 s34, 0x1fff
	s_cselect_b32 s34, s12, 0x2400
	s_barrier
	s_ashr_i32 s35, s34, 31
	s_waitcnt vmcnt(15)
	v_lshrrev_b32_e32 v64, 6, v144
	s_waitcnt vmcnt(9)
	v_mul_lo_u32 v68, v64, s45
	v_lshrrev_b32_e32 v64, 3, v144
	s_lshl_b64 s[34:35], s[34:35], 2
	v_and_b32_e32 v64, 4, v64
	s_add_u32 s37, s10, s34
	v_cvt_pk_bf16_f32 v48, v48, v49
	v_cvt_pk_bf16_f32 v49, v50, v51
	v_mul_u32_u24_e32 v50, 0x48, v64
	s_addc_u32 s38, s11, s35
	s_lshl_b64 s[34:35], s[30:31], 1
	v_lshlrev_b32_e32 v65, 1, v144
	v_lshl_add_u32 v50, v50, 1, v68
	s_add_u32 s12, s42, s34
	v_and_or_b32 v69, v65, 62, v50
	s_addc_u32 s36, s43, s35
	s_lshl_b64 s[30:31], s[30:31], 2
	ds_write_b16 v69, v48
	ds_write_b16_d16_hi v69, v48 offset:144
	ds_write_b16 v69, v49 offset:288
	ds_write_b16_d16_hi v69, v49 offset:432
	v_cvt_pk_bf16_f32 v48, v52, v53
	v_cvt_pk_bf16_f32 v49, v54, v55
	s_add_u32 s30, s8, s30
	ds_write_b16 v69, v48 offset:1152
	ds_write_b16_d16_hi v69, v48 offset:1296
	ds_write_b16 v69, v49 offset:1440
	ds_write_b16_d16_hi v69, v49 offset:1584
	v_cvt_pk_bf16_f32 v48, v56, v57
	v_cvt_pk_bf16_f32 v49, v58, v59
	s_addc_u32 s31, s9, s31
	s_lshl_b32 s34, s49, 2
	ds_write_b16 v69, v48 offset:2304
	ds_write_b16_d16_hi v69, v48 offset:2448
	ds_write_b16 v69, v49 offset:2592
	ds_write_b16_d16_hi v69, v49 offset:2736
	v_cvt_pk_bf16_f32 v48, v60, v61
	v_cvt_pk_bf16_f32 v49, v62, v63
	v_cvt_pk_bf16_f32 v32, v32, v33
	s_add_u32 s30, s30, s34
	ds_write_b16 v69, v48 offset:3456
	ds_write_b16_d16_hi v69, v48 offset:3600
	ds_write_b16 v69, v49 offset:3744
	ds_write_b16_d16_hi v69, v49 offset:3888
	v_cvt_pk_bf16_f32 v49, v34, v35
	ds_write_b16 v69, v32 offset:64
	ds_write_b16_d16_hi v69, v32 offset:208
	ds_write_b16 v69, v49 offset:352
	v_lshlrev_b32_e32 v32, 3, v144
	s_addc_u32 s31, s31, 0
	v_and_b32_e32 v70, 56, v32
	s_add_u32 s34, s37, s34
	v_and_or_b32 v48, v144, 64, v70
	s_addc_u32 s35, s38, 0
	v_ashrrev_i32_e32 v32, 1, v144
	v_lshlrev_b32_e32 v128, 2, v48
	v_bfe_u32 v71, v144, 3, 3
	v_lshl_add_u64 v[62:63], s[34:35], 0, v[128:129]
	v_and_or_b32 v32, v32, s46, v71
	v_ashrrev_i32_e32 v33, 31, v32
	v_add_co_u32_e32 v34, vcc, s47, v62
	v_lshlrev_b64 v[66:67], 10, v[32:33]
	s_nop 0
	v_addc_co_u32_e32 v35, vcc, 0, v63, vcc
	global_load_dwordx4 v[50:53], v[34:35], off
	v_or_b32_e32 v66, v66, v48
	v_lshl_add_u64 v[64:65], v[66:67], 2, s[30:31]
	global_load_dwordx4 v[54:57], v[64:65], off offset:16
	global_load_dwordx4 v[58:61], v[64:65], off
	v_cvt_pk_bf16_f32 v33, v36, v37
	ds_write_b16_d16_hi v69, v49 offset:496
	v_cvt_pk_bf16_f32 v38, v38, v39
	ds_write_b16 v69, v33 offset:1216
	ds_write_b16_d16_hi v69, v33 offset:1360
	ds_write_b16 v69, v38 offset:1504
	v_lshl_add_u64 v[36:37], v[62:63], 0, s[26:27]
	global_load_dwordx4 v[62:65], v[36:37], off offset:16
	v_or_b32_e32 v130, 8, v32
	v_lshl_or_b32 v130, v130, 10, v48
	v_lshlrev_b32_e32 v130, 2, v130
	global_load_dwordx4 v[72:75], v130, s[30:31]
	global_load_dwordx4 v[76:79], v130, s[30:31] offset:16
	v_or_b32_e32 v130, 16, v32
	v_lshl_or_b32 v130, v130, 10, v48
	v_lshlrev_b32_e32 v130, 2, v130
	global_load_dwordx4 v[80:83], v130, s[30:31]
	global_load_dwordx4 v[84:87], v130, s[30:31] offset:16
	v_or_b32_e32 v130, 24, v32
	v_lshl_or_b32 v130, v130, 10, v48
	v_lshlrev_b32_e32 v130, 2, v130
	global_load_dwordx4 v[88:91], v130, s[30:31]
	global_load_dwordx4 v[92:95], v130, s[30:31] offset:16
	v_or_b32_e32 v130, 32, v32
	v_lshl_or_b32 v130, v130, 10, v48
	v_lshlrev_b32_e32 v130, 2, v130
	global_load_dwordx4 v[96:99], v130, s[30:31]
	global_load_dwordx4 v[100:103], v130, s[30:31] offset:16
	v_or_b32_e32 v130, 40, v32
	v_lshl_or_b32 v130, v130, 10, v48
	v_lshlrev_b32_e32 v130, 2, v130
	global_load_dwordx4 v[104:107], v130, s[30:31]
	global_load_dwordx4 v[108:111], v130, s[30:31] offset:16
	v_or_b32_e32 v130, 48, v32
	v_lshl_or_b32 v130, v130, 10, v48
	v_lshlrev_b32_e32 v130, 2, v130
	global_load_dwordx4 v[112:115], v130, s[30:31]
	global_load_dwordx4 v[116:119], v130, s[30:31] offset:16
	v_or_b32_e32 v130, 56, v32
	v_lshl_or_b32 v130, v130, 10, v48
	v_lshlrev_b32_e32 v130, 2, v130
	global_load_dwordx4 v[120:123], v130, s[30:31]
	global_load_dwordx4 v[124:127], v130, s[30:31] offset:16
	v_cvt_pk_bf16_f32 v33, v40, v41
	ds_write_b16_d16_hi v69, v38 offset:1648
	v_cvt_pk_bf16_f32 v38, v42, v43
	ds_write_b16 v69, v33 offset:2368
	ds_write_b16_d16_hi v69, v33 offset:2512
	ds_write_b16 v69, v38 offset:2656
	ds_write_b16_d16_hi v69, v38 offset:2800
	v_cvt_pk_bf16_f32 v33, v44, v45
	v_cvt_pk_bf16_f32 v16, v16, v17
	v_cvt_pk_bf16_f32 v38, v46, v47
	ds_write_b16 v69, v33 offset:3520
	ds_write_b16_d16_hi v69, v33 offset:3664
	ds_write_b16 v69, v38 offset:3808
	ds_write_b16_d16_hi v69, v38 offset:3952
	v_cvt_pk_bf16_f32 v17, v18, v19
	ds_write_b16 v69, v16 offset:4608
	ds_write_b16_d16_hi v69, v16 offset:4752
	ds_write_b16 v69, v17 offset:4896
	ds_write_b16_d16_hi v69, v17 offset:5040
	v_cvt_pk_bf16_f32 v16, v20, v21
	v_cvt_pk_bf16_f32 v17, v22, v23
	ds_write_b16 v69, v16 offset:5760
	ds_write_b16_d16_hi v69, v16 offset:5904
	ds_write_b16 v69, v17 offset:6048
	ds_write_b16_d16_hi v69, v17 offset:6192
	v_cvt_pk_bf16_f32 v16, v24, v25
	v_cvt_pk_bf16_f32 v17, v26, v27
	ds_write_b16 v69, v16 offset:6912
	ds_write_b16_d16_hi v69, v16 offset:7056
	ds_write_b16 v69, v17 offset:7200
	ds_write_b16_d16_hi v69, v17 offset:7344
	v_cvt_pk_bf16_f32 v16, v28, v29
	v_cvt_pk_bf16_f32 v0, v0, v1
	v_cvt_pk_bf16_f32 v17, v30, v31
	ds_write_b16 v69, v16 offset:8064
	ds_write_b16_d16_hi v69, v16 offset:8208
	ds_write_b16 v69, v17 offset:8352
	ds_write_b16_d16_hi v69, v17 offset:8496
	v_cvt_pk_bf16_f32 v1, v2, v3
	ds_write_b16 v69, v0 offset:4672
	ds_write_b16_d16_hi v69, v0 offset:4816
	ds_write_b16 v69, v1 offset:4960
	ds_write_b16_d16_hi v69, v1 offset:5104
	v_cvt_pk_bf16_f32 v0, v4, v5
	v_cvt_pk_bf16_f32 v1, v6, v7
	ds_write_b16 v69, v0 offset:5824
	ds_write_b16_d16_hi v69, v0 offset:5968
	ds_write_b16 v69, v1 offset:6112
	ds_write_b16_d16_hi v69, v1 offset:6256
	v_cvt_pk_bf16_f32 v0, v8, v9
	v_cvt_pk_bf16_f32 v1, v10, v11
	ds_write_b16 v69, v0 offset:6976
	ds_write_b16_d16_hi v69, v0 offset:7120
	ds_write_b16 v69, v1 offset:7264
	ds_write_b16_d16_hi v69, v1 offset:7408
	v_cvt_pk_bf16_f32 v0, v12, v13
	v_cvt_pk_bf16_f32 v1, v14, v15
	ds_write_b16 v69, v0 offset:8128
	ds_write_b16_d16_hi v69, v0 offset:8272
	ds_write_b16 v69, v1 offset:8416
	ds_write_b16_d16_hi v69, v1 offset:8560
	v_lshl_or_b32 v0, v70, 1, v68
	v_mad_u32_u24 v0, v71, s44, v0
	ds_read_b128 v[2:5], v0
	s_lshl_b32 s37, s49, 1
	s_add_u32 s34, s12, s37
	s_addc_u32 s35, s36, 0
	ds_read_b128 v[6:9], v0 offset:1152
	s_waitcnt lgkmcnt(1)
	v_lshlrev_b32_e32 v12, 16, v2
	v_and_b32_e32 v13, 0xffff0000, v2
	s_waitcnt vmcnt(14)
	v_pk_add_f32 v[10:11], v[50:51], 1.0 op_sel_hi:[1,0]
	s_nop 0
	v_pk_mul_f32 v[10:11], v[10:11], v[12:13]
	v_lshlrev_b32_e32 v12, 16, v3
	v_pk_fma_f32 v[10:11], v[58:59], s[28:29], v[10:11] op_sel_hi:[1,0,1]
	v_and_b32_e32 v13, 0xffff0000, v3
	v_cvt_pk_bf16_f32 v2, v10, v11
	v_pk_add_f32 v[10:11], v[52:53], 1.0 op_sel_hi:[1,0]
	s_nop 0
	v_pk_mul_f32 v[10:11], v[10:11], v[12:13]
	v_lshlrev_b32_e32 v12, 16, v4
	v_pk_fma_f32 v[10:11], v[60:61], s[28:29], v[10:11] op_sel_hi:[1,0,1]
	v_and_b32_e32 v13, 0xffff0000, v4
	v_cvt_pk_bf16_f32 v3, v10, v11
	v_pk_add_f32 v[10:11], v[62:63], 1.0 op_sel_hi:[1,0]
	s_nop 0
	v_pk_mul_f32 v[10:11], v[10:11], v[12:13]
	v_lshlrev_b32_e32 v12, 16, v5
	v_pk_fma_f32 v[10:11], v[54:55], s[28:29], v[10:11] op_sel_hi:[1,0,1]
	v_and_b32_e32 v13, 0xffff0000, v5
	v_cvt_pk_bf16_f32 v4, v10, v11
	v_pk_add_f32 v[10:11], v[64:65], 1.0 op_sel_hi:[1,0]
	s_nop 0
	v_pk_mul_f32 v[10:11], v[10:11], v[12:13]
	s_nop 0
	v_pk_fma_f32 v[10:11], v[56:57], s[28:29], v[10:11] op_sel_hi:[1,0,1]
	s_nop 0
	v_cvt_pk_bf16_f32 v5, v10, v11
	v_lshl_add_u64 v[10:11], v[66:67], 1, s[34:35]
	s_waitcnt vmcnt(0)
	global_store_dwordx4 v[10:11], v[2:5], off
	v_or_b32_e32 v10, 8, v32
	v_ashrrev_i32_e32 v11, 31, v10
	v_lshlrev_b64 v[22:23], 10, v[10:11]
	v_or_b32_e32 v22, v22, v48
	v_lshl_add_u64 v[24:25], v[22:23], 2, s[30:31]
	s_waitcnt lgkmcnt(0)
	v_lshlrev_b32_e32 v24, 16, v6
	v_and_b32_e32 v25, 0xffff0000, v6
	v_lshlrev_b32_e32 v6, 16, v7
	v_and_b32_e32 v7, 0xffff0000, v7
	v_pk_add_f32 v[2:3], v[50:51], 1.0 op_sel_hi:[1,0]
	v_pk_add_f32 v[4:5], v[52:53], 1.0 op_sel_hi:[1,0]
	v_pk_mul_f32 v[2:3], v[2:3], v[24:25]
	v_pk_mul_f32 v[4:5], v[4:5], v[6:7]
	v_pk_fma_f32 v[2:3], v[72:73], s[28:29], v[2:3] op_sel_hi:[1,0,1]
	v_pk_fma_f32 v[4:5], v[74:75], s[28:29], v[4:5] op_sel_hi:[1,0,1]
	v_cvt_pk_bf16_f32 v2, v2, v3
	v_cvt_pk_bf16_f32 v3, v4, v5
	v_pk_add_f32 v[4:5], v[62:63], 1.0 op_sel_hi:[1,0]
	v_lshlrev_b32_e32 v6, 16, v8
	v_and_b32_e32 v7, 0xffff0000, v8
	v_pk_mul_f32 v[4:5], v[4:5], v[6:7]
	v_pk_add_f32 v[6:7], v[64:65], 1.0 op_sel_hi:[1,0]
	v_lshlrev_b32_e32 v8, 16, v9
	v_and_b32_e32 v9, 0xffff0000, v9
	v_pk_mul_f32 v[6:7], v[6:7], v[8:9]
	v_pk_fma_f32 v[4:5], v[76:77], s[28:29], v[4:5] op_sel_hi:[1,0,1]
	v_pk_fma_f32 v[6:7], v[78:79], s[28:29], v[6:7] op_sel_hi:[1,0,1]
	v_or_b32_e32 v10, 16, v32
	v_cvt_pk_bf16_f32 v4, v4, v5
	v_cvt_pk_bf16_f32 v5, v6, v7
	v_lshl_add_u64 v[6:7], v[22:23], 1, s[34:35]
	v_ashrrev_i32_e32 v11, 31, v10
	global_store_dwordx4 v[6:7], v[2:5], off
	v_lshlrev_b64 v[26:27], 10, v[10:11]
	v_or_b32_e32 v26, v26, v48
	v_lshl_add_u64 v[18:19], v[26:27], 2, s[30:31]
	ds_read_b128 v[18:21], v0 offset:2304
	ds_read_b128 v[22:25], v0 offset:3456
	v_lshl_add_u64 v[26:27], v[26:27], 1, s[34:35]
	s_waitcnt lgkmcnt(1)
	v_lshlrev_b32_e32 v28, 16, v18
	v_and_b32_e32 v29, 0xffff0000, v18
	v_lshlrev_b32_e32 v18, 16, v19
	v_and_b32_e32 v19, 0xffff0000, v19
	v_lshlrev_b32_e32 v30, 16, v20
	v_and_b32_e32 v31, 0xffff0000, v20
	v_lshlrev_b32_e32 v20, 16, v21
	v_and_b32_e32 v21, 0xffff0000, v21
	v_pk_add_f32 v[2:3], v[50:51], 1.0 op_sel_hi:[1,0]
	v_pk_add_f32 v[4:5], v[52:53], 1.0 op_sel_hi:[1,0]
	v_pk_add_f32 v[6:7], v[62:63], 1.0 op_sel_hi:[1,0]
	v_pk_add_f32 v[8:9], v[64:65], 1.0 op_sel_hi:[1,0]
	v_pk_mul_f32 v[2:3], v[2:3], v[28:29]
	v_pk_mul_f32 v[4:5], v[4:5], v[18:19]
	v_pk_mul_f32 v[6:7], v[6:7], v[30:31]
	v_pk_mul_f32 v[8:9], v[8:9], v[20:21]
	v_pk_fma_f32 v[2:3], v[80:81], s[28:29], v[2:3] op_sel_hi:[1,0,1]
	v_pk_fma_f32 v[4:5], v[82:83], s[28:29], v[4:5] op_sel_hi:[1,0,1]
	v_pk_fma_f32 v[6:7], v[84:85], s[28:29], v[6:7] op_sel_hi:[1,0,1]
	v_pk_fma_f32 v[8:9], v[86:87], s[28:29], v[8:9] op_sel_hi:[1,0,1]
	v_or_b32_e32 v10, 24, v32
	v_cvt_pk_bf16_f32 v2, v2, v3
	v_cvt_pk_bf16_f32 v3, v4, v5
	v_cvt_pk_bf16_f32 v4, v6, v7
	v_cvt_pk_bf16_f32 v5, v8, v9
	v_ashrrev_i32_e32 v11, 31, v10
	global_store_dwordx4 v[26:27], v[2:5], off
	v_lshlrev_b64 v[18:19], 10, v[10:11]
	v_or_b32_e32 v18, v18, v48
	v_lshl_add_u64 v[20:21], v[18:19], 2, s[30:31]
	s_waitcnt lgkmcnt(0)
	v_lshlrev_b32_e32 v20, 16, v22
	v_and_b32_e32 v21, 0xffff0000, v22
	v_lshlrev_b32_e32 v22, 16, v23
	v_and_b32_e32 v23, 0xffff0000, v23
	v_lshlrev_b32_e32 v26, 16, v24
	v_and_b32_e32 v27, 0xffff0000, v24
	v_lshlrev_b32_e32 v24, 16, v25
	v_and_b32_e32 v25, 0xffff0000, v25
	v_lshl_add_u64 v[18:19], v[18:19], 1, s[34:35]
	v_pk_add_f32 v[2:3], v[50:51], 1.0 op_sel_hi:[1,0]
	v_pk_add_f32 v[4:5], v[52:53], 1.0 op_sel_hi:[1,0]
	v_pk_add_f32 v[6:7], v[62:63], 1.0 op_sel_hi:[1,0]
	v_pk_add_f32 v[8:9], v[64:65], 1.0 op_sel_hi:[1,0]
	v_pk_mul_f32 v[2:3], v[2:3], v[20:21]
	v_pk_mul_f32 v[4:5], v[4:5], v[22:23]
	v_pk_mul_f32 v[6:7], v[6:7], v[26:27]
	v_pk_mul_f32 v[8:9], v[8:9], v[24:25]
	v_pk_fma_f32 v[2:3], v[88:89], s[28:29], v[2:3] op_sel_hi:[1,0,1]
	v_pk_fma_f32 v[4:5], v[90:91], s[28:29], v[4:5] op_sel_hi:[1,0,1]
	v_pk_fma_f32 v[6:7], v[92:93], s[28:29], v[6:7] op_sel_hi:[1,0,1]
	v_pk_fma_f32 v[8:9], v[94:95], s[28:29], v[8:9] op_sel_hi:[1,0,1]
	v_or_b32_e32 v10, 32, v32
	v_cvt_pk_bf16_f32 v2, v2, v3
	v_cvt_pk_bf16_f32 v3, v4, v5
	v_cvt_pk_bf16_f32 v4, v6, v7
	v_cvt_pk_bf16_f32 v5, v8, v9
	v_ashrrev_i32_e32 v11, 31, v10
	global_store_dwordx4 v[18:19], v[2:5], off
	v_lshlrev_b64 v[26:27], 10, v[10:11]
	v_or_b32_e32 v26, v26, v48
	v_lshl_add_u64 v[18:19], v[26:27], 2, s[30:31]
	ds_read_b128 v[18:21], v0 offset:4608
	ds_read_b128 v[22:25], v0 offset:5760
	v_lshl_add_u64 v[26:27], v[26:27], 1, s[34:35]
	s_waitcnt lgkmcnt(1)
	v_lshlrev_b32_e32 v28, 16, v18
	v_and_b32_e32 v29, 0xffff0000, v18
	v_lshlrev_b32_e32 v18, 16, v19
	v_and_b32_e32 v19, 0xffff0000, v19
	v_lshlrev_b32_e32 v30, 16, v20
	v_and_b32_e32 v31, 0xffff0000, v20
	v_lshlrev_b32_e32 v20, 16, v21
	v_and_b32_e32 v21, 0xffff0000, v21
	v_pk_add_f32 v[2:3], v[50:51], 1.0 op_sel_hi:[1,0]
	v_pk_add_f32 v[4:5], v[52:53], 1.0 op_sel_hi:[1,0]
	v_pk_add_f32 v[6:7], v[62:63], 1.0 op_sel_hi:[1,0]
	v_pk_add_f32 v[8:9], v[64:65], 1.0 op_sel_hi:[1,0]
	v_pk_mul_f32 v[2:3], v[2:3], v[28:29]
	v_pk_mul_f32 v[4:5], v[4:5], v[18:19]
	v_pk_mul_f32 v[6:7], v[6:7], v[30:31]
	v_pk_mul_f32 v[8:9], v[8:9], v[20:21]
	v_pk_fma_f32 v[2:3], v[96:97], s[28:29], v[2:3] op_sel_hi:[1,0,1]
	v_pk_fma_f32 v[4:5], v[98:99], s[28:29], v[4:5] op_sel_hi:[1,0,1]
	v_pk_fma_f32 v[6:7], v[100:101], s[28:29], v[6:7] op_sel_hi:[1,0,1]
	v_pk_fma_f32 v[8:9], v[102:103], s[28:29], v[8:9] op_sel_hi:[1,0,1]
	v_or_b32_e32 v10, 40, v32
	v_cvt_pk_bf16_f32 v2, v2, v3
	v_cvt_pk_bf16_f32 v3, v4, v5
	v_cvt_pk_bf16_f32 v4, v6, v7
	v_cvt_pk_bf16_f32 v5, v8, v9
	v_ashrrev_i32_e32 v11, 31, v10
	global_store_dwordx4 v[26:27], v[2:5], off
	v_lshlrev_b64 v[18:19], 10, v[10:11]
	v_or_b32_e32 v18, v18, v48
	v_lshl_add_u64 v[20:21], v[18:19], 2, s[30:31]
	s_waitcnt lgkmcnt(0)
	v_lshlrev_b32_e32 v20, 16, v22
	v_and_b32_e32 v21, 0xffff0000, v22
	v_lshlrev_b32_e32 v22, 16, v23
	v_and_b32_e32 v23, 0xffff0000, v23
	v_lshlrev_b32_e32 v26, 16, v24
	v_and_b32_e32 v27, 0xffff0000, v24
	v_lshlrev_b32_e32 v24, 16, v25
	v_and_b32_e32 v25, 0xffff0000, v25
	v_lshl_add_u64 v[18:19], v[18:19], 1, s[34:35]
	v_pk_add_f32 v[2:3], v[50:51], 1.0 op_sel_hi:[1,0]
	v_pk_add_f32 v[4:5], v[52:53], 1.0 op_sel_hi:[1,0]
	v_pk_add_f32 v[6:7], v[62:63], 1.0 op_sel_hi:[1,0]
	v_pk_add_f32 v[8:9], v[64:65], 1.0 op_sel_hi:[1,0]
	v_pk_mul_f32 v[2:3], v[2:3], v[20:21]
	v_pk_mul_f32 v[4:5], v[4:5], v[22:23]
	v_pk_mul_f32 v[6:7], v[6:7], v[26:27]
	v_pk_mul_f32 v[8:9], v[8:9], v[24:25]
	v_pk_fma_f32 v[2:3], v[104:105], s[28:29], v[2:3] op_sel_hi:[1,0,1]
	v_pk_fma_f32 v[4:5], v[106:107], s[28:29], v[4:5] op_sel_hi:[1,0,1]
	v_pk_fma_f32 v[6:7], v[108:109], s[28:29], v[6:7] op_sel_hi:[1,0,1]
	v_pk_fma_f32 v[8:9], v[110:111], s[28:29], v[8:9] op_sel_hi:[1,0,1]
	v_or_b32_e32 v10, 48, v32
	v_cvt_pk_bf16_f32 v2, v2, v3
	v_cvt_pk_bf16_f32 v3, v4, v5
	v_cvt_pk_bf16_f32 v4, v6, v7
	v_cvt_pk_bf16_f32 v5, v8, v9
	v_ashrrev_i32_e32 v11, 31, v10
	global_store_dwordx4 v[18:19], v[2:5], off
	v_lshlrev_b64 v[26:27], 10, v[10:11]
	v_or_b32_e32 v26, v26, v48
	v_lshl_add_u64 v[18:19], v[26:27], 2, s[30:31]
	ds_read_b128 v[18:21], v0 offset:6912
	ds_read_b128 v[22:25], v0 offset:8064
	v_lshl_add_u64 v[26:27], v[26:27], 1, s[34:35]
	s_waitcnt lgkmcnt(1)
	v_lshlrev_b32_e32 v0, 16, v18
	v_and_b32_e32 v1, 0xffff0000, v18
	v_lshlrev_b32_e32 v18, 16, v19
	v_and_b32_e32 v19, 0xffff0000, v19
	v_lshlrev_b32_e32 v28, 16, v20
	v_and_b32_e32 v29, 0xffff0000, v20
	v_lshlrev_b32_e32 v20, 16, v21
	v_and_b32_e32 v21, 0xffff0000, v21
	v_pk_add_f32 v[2:3], v[50:51], 1.0 op_sel_hi:[1,0]
	v_pk_add_f32 v[4:5], v[52:53], 1.0 op_sel_hi:[1,0]
	v_pk_add_f32 v[6:7], v[62:63], 1.0 op_sel_hi:[1,0]
	v_pk_add_f32 v[8:9], v[64:65], 1.0 op_sel_hi:[1,0]
	v_pk_mul_f32 v[0:1], v[2:3], v[0:1]
	v_pk_mul_f32 v[2:3], v[4:5], v[18:19]
	v_pk_mul_f32 v[4:5], v[6:7], v[28:29]
	v_pk_mul_f32 v[6:7], v[8:9], v[20:21]
	v_pk_fma_f32 v[0:1], v[112:113], s[28:29], v[0:1] op_sel_hi:[1,0,1]
	v_pk_fma_f32 v[2:3], v[114:115], s[28:29], v[2:3] op_sel_hi:[1,0,1]
	v_pk_fma_f32 v[4:5], v[116:117], s[28:29], v[4:5] op_sel_hi:[1,0,1]
	v_pk_fma_f32 v[6:7], v[118:119], s[28:29], v[6:7] op_sel_hi:[1,0,1]
	v_or_b32_e32 v8, 56, v32
	v_cvt_pk_bf16_f32 v0, v0, v1
	v_cvt_pk_bf16_f32 v1, v2, v3
	v_cvt_pk_bf16_f32 v2, v4, v5
	v_cvt_pk_bf16_f32 v3, v6, v7
	v_ashrrev_i32_e32 v9, 31, v8
	global_store_dwordx4 v[26:27], v[0:3], off
	v_lshlrev_b64 v[16:17], 10, v[8:9]
	v_or_b32_e32 v16, v16, v48
	v_lshl_add_u64 v[18:19], v[16:17], 2, s[30:31]
	s_waitcnt lgkmcnt(0)
	v_lshlrev_b32_e32 v18, 16, v22
	v_and_b32_e32 v19, 0xffff0000, v22
	v_lshlrev_b32_e32 v20, 16, v23
	v_and_b32_e32 v21, 0xffff0000, v23
	v_lshlrev_b32_e32 v22, 16, v24
	v_and_b32_e32 v23, 0xffff0000, v24
	v_lshlrev_b32_e32 v24, 16, v25
	v_and_b32_e32 v25, 0xffff0000, v25
	v_pk_add_f32 v[0:1], v[50:51], 1.0 op_sel_hi:[1,0]
	v_pk_add_f32 v[2:3], v[52:53], 1.0 op_sel_hi:[1,0]
	v_pk_add_f32 v[4:5], v[62:63], 1.0 op_sel_hi:[1,0]
	v_pk_add_f32 v[6:7], v[64:65], 1.0 op_sel_hi:[1,0]
	v_pk_mul_f32 v[0:1], v[0:1], v[18:19]
	v_pk_mul_f32 v[2:3], v[2:3], v[20:21]
	v_pk_mul_f32 v[4:5], v[4:5], v[22:23]
	v_pk_mul_f32 v[6:7], v[6:7], v[24:25]
	v_pk_fma_f32 v[0:1], v[120:121], s[28:29], v[0:1] op_sel_hi:[1,0,1]
	v_pk_fma_f32 v[2:3], v[122:123], s[28:29], v[2:3] op_sel_hi:[1,0,1]
	v_pk_fma_f32 v[4:5], v[124:125], s[28:29], v[4:5] op_sel_hi:[1,0,1]
	v_pk_fma_f32 v[6:7], v[126:127], s[28:29], v[6:7] op_sel_hi:[1,0,1]
	v_cvt_pk_bf16_f32 v0, v0, v1
	v_cvt_pk_bf16_f32 v1, v2, v3
	v_cvt_pk_bf16_f32 v2, v4, v5
	v_cvt_pk_bf16_f32 v3, v6, v7
	v_lshl_add_u64 v[4:5], v[16:17], 1, s[34:35]
	global_store_dwordx4 v[4:5], v[0:3], off
	s_load_dword s12, s[16:17], 0x0
	s_waitcnt lgkmcnt(0)
	s_add_i32 s48, s12, s48
	s_cmpk_lt_i32 s48, 0x400
	s_cbranch_scc1 .LBB0_1465
	s_load_dword s3, s[0:1], 0x10c
	s_waitcnt lgkmcnt(0)
	v_mov_b32_e32 v10, s3
